# v29 with the GEMM k-loop head labels aligned to 64 bytes (code placement)
# baseline (speedup 1.0000x reference)
; DI f32x4 mfma16(bf16x8 a, bf16x8 b, f32x4 c) { return __builtin_amdgcn_mfma_f32_16x16x32_bf16(a, b, c, 0, 0, 0); }
; template <int MI, int NJ, bool SWAP, class AP, class BP>
; DI void gemm_main(f32x4 (&acc)[MI][NJ], const AP& ap, int a_kstep, const BP& bp, int b_kstep, int nk, bf16_t* smem) {
;     ...
;   for (int kt = 0; kt < nk; ++kt) {
;     const int buf = kt & 1;
;     sstore(buf ^ 1);
;     gload(kt + 2 < nk ? kt + 2 : nk - 1);
;     __builtin_amdgcn_sched_barrier(0);
;     const bf16_t* As = smem + buf * L::STAGE + (wm * 16 * MI + l15) * LDT + quad * 8;
;     const bf16_t* Bs = smem + buf * L::STAGE + L::A_ELEMS + (wn * 16 * NJ + l15) * LDT + quad * 8;
; #pragma unroll
;     for (int ks = 0; ks < 2; ++ks) {
;       if (MI * NJ >= 32 && ks == 1) asm volatile("" ::: "memory");
;       bf16x8 b[NJ];
; #pragma unroll
;       for (int j = 0; j < NJ; ++j) b[j] = *(const bf16x8*)(Bs + j * 16 * LDT + ks * 32);
; #pragma unroll
;       for (int i = 0; i < MI; ++i) {
;         const bf16x8 a = *(const bf16x8*)(As + i * 16 * LDT + ks * 32);
; #pragma unroll
;         for (int j = 0; j < NJ; ++j) acc[i][j] = SWAP ? mfma16(b[j], a, acc[i][j]) : mfma16(a, b[j], acc[i][j]);
.LBB0_174:
	s_and_b32 s98, s4, 1
	s_mul_i32 s98, s98, 0x12000
	v_add3_u32 v182, s98, v168, v172
	v_add3_u32 v176, s98, v170, v172
	ds_read_b128 v[212:215], v176
	ds_read_b128 v[216:219], v176 offset:2304
	ds_read_b128 v[178:181], v182 offset:36864
	ds_read_b128 v[200:203], v182 offset:39168
	ds_read_b128 v[204:207], v182 offset:41472
	ds_read_b128 v[208:211], v182 offset:43776
	.p2align 6

; DI f32x4 mfma16(bf16x8 a, bf16x8 b, f32x4 c) { return __builtin_amdgcn_mfma_f32_16x16x32_bf16(a, b, c, 0, 0, 0); }
; template <int MI, int NJ, bool SWAP, class AP, class BP>
; DI void gemm_main(f32x4 (&acc)[MI][NJ], const AP& ap, int a_kstep, const BP& bp, int b_kstep, int nk, bf16_t* smem) {
;     ...
;   for (int kt = 0; kt < nk; ++kt) {
;     const int buf = kt & 1;
;     sstore(buf ^ 1);
;     gload(kt + 2 < nk ? kt + 2 : nk - 1);
;     __builtin_amdgcn_sched_barrier(0);
;     const bf16_t* As = smem + buf * L::STAGE + (wm * 16 * MI + l15) * LDT + quad * 8;
;     const bf16_t* Bs = smem + buf * L::STAGE + L::A_ELEMS + (wn * 16 * NJ + l15) * LDT + quad * 8;
; #pragma unroll
;     for (int ks = 0; ks < 2; ++ks) {
;       if (MI * NJ >= 32 && ks == 1) asm volatile("" ::: "memory");
;       bf16x8 b[NJ];
; #pragma unroll
;       for (int j = 0; j < NJ; ++j) b[j] = *(const bf16x8*)(Bs + j * 16 * LDT + ks * 32);
; #pragma unroll
;       for (int i = 0; i < MI; ++i) {
;         const bf16x8 a = *(const bf16x8*)(As + i * 16 * LDT + ks * 32);
; #pragma unroll
;         for (int j = 0; j < NJ; ++j) acc[i][j] = SWAP ? mfma16(b[j], a, acc[i][j]) : mfma16(a, b[j], acc[i][j]);
.LBB0_297:
	s_and_b32 s98, s4, 1
	s_mul_i32 s98, s98, 0x12000
	v_add3_u32 v176, s98, v174, v175
	v_add3_u32 v182, s98, v169, v175
	ds_read_b128 v[212:215], v176
	ds_read_b128 v[216:219], v176 offset:2304
	ds_read_b128 v[178:181], v182 offset:36864
	ds_read_b128 v[200:203], v182 offset:39168
	ds_read_b128 v[204:207], v182 offset:41472
	ds_read_b128 v[208:211], v182 offset:43776
	.p2align 6

; DI f32x4 mfma16(bf16x8 a, bf16x8 b, f32x4 c) { return __builtin_amdgcn_mfma_f32_16x16x32_bf16(a, b, c, 0, 0, 0); }
; template <int MI, int NJ, bool SWAP, class AP, class BP>
; DI void gemm_main(f32x4 (&acc)[MI][NJ], const AP& ap, int a_kstep, const BP& bp, int b_kstep, int nk, bf16_t* smem) {
;     ...
;   for (int kt = 0; kt < nk; ++kt) {
;     const int buf = kt & 1;
;     sstore(buf ^ 1);
;     gload(kt + 2 < nk ? kt + 2 : nk - 1);
;     __builtin_amdgcn_sched_barrier(0);
;     const bf16_t* As = smem + buf * L::STAGE + (wm * 16 * MI + l15) * LDT + quad * 8;
;     const bf16_t* Bs = smem + buf * L::STAGE + L::A_ELEMS + (wn * 16 * NJ + l15) * LDT + quad * 8;
; #pragma unroll
;     for (int ks = 0; ks < 2; ++ks) {
;       if (MI * NJ >= 32 && ks == 1) asm volatile("" ::: "memory");
;       bf16x8 b[NJ];
; #pragma unroll
;       for (int j = 0; j < NJ; ++j) b[j] = *(const bf16x8*)(Bs + j * 16 * LDT + ks * 32);
; #pragma unroll
;       for (int i = 0; i < MI; ++i) {
;         const bf16x8 a = *(const bf16x8*)(As + i * 16 * LDT + ks * 32);
; #pragma unroll
;         for (int j = 0; j < NJ; ++j) acc[i][j] = SWAP ? mfma16(b[j], a, acc[i][j]) : mfma16(a, b[j], acc[i][j]);
.LBB0_376:
	s_and_b32 s98, s16, 1
	s_mul_i32 s98, s98, 0x12000
	v_add3_u32 v183, s98, v160, v177
	v_add3_u32 v182, s98, v172, v177
	ds_read_b128 v[198:201], v182
	ds_read_b128 v[202:205], v182 offset:2304
	ds_read_b128 v[178:181], v183 offset:36864
	ds_read_b128 v[186:189], v183 offset:39168
	ds_read_b128 v[190:193], v183 offset:41472
	ds_read_b128 v[194:197], v183 offset:43776
	.p2align 6

; DI f32x4 mfma16(bf16x8 a, bf16x8 b, f32x4 c) { return __builtin_amdgcn_mfma_f32_16x16x32_bf16(a, b, c, 0, 0, 0); }
; template <int MI, int NJ, bool SWAP, class AP, class BP>
; DI void gemm_main(f32x4 (&acc)[MI][NJ], const AP& ap, int a_kstep, const BP& bp, int b_kstep, int nk, bf16_t* smem) {
;     ...
;   for (int kt = 0; kt < nk; ++kt) {
;     const int buf = kt & 1;
;     sstore(buf ^ 1);
;     gload(kt + 2 < nk ? kt + 2 : nk - 1);
;     __builtin_amdgcn_sched_barrier(0);
;     const bf16_t* As = smem + buf * L::STAGE + (wm * 16 * MI + l15) * LDT + quad * 8;
;     const bf16_t* Bs = smem + buf * L::STAGE + L::A_ELEMS + (wn * 16 * NJ + l15) * LDT + quad * 8;
; #pragma unroll
;     for (int ks = 0; ks < 2; ++ks) {
;       if (MI * NJ >= 32 && ks == 1) asm volatile("" ::: "memory");
;       bf16x8 b[NJ];
; #pragma unroll
;       for (int j = 0; j < NJ; ++j) b[j] = *(const bf16x8*)(Bs + j * 16 * LDT + ks * 32);
; #pragma unroll
;       for (int i = 0; i < MI; ++i) {
;         const bf16x8 a = *(const bf16x8*)(As + i * 16 * LDT + ks * 32);
; #pragma unroll
;         for (int j = 0; j < NJ; ++j) acc[i][j] = SWAP ? mfma16(b[j], a, acc[i][j]) : mfma16(a, b[j], acc[i][j]);
.LBB0_396:
	s_and_b32 s98, s33, 1
	s_mul_i32 s98, s98, 0x12000
	v_add3_u32 v183, s98, v171, v177
	v_add3_u32 v182, s98, v176, v177
	ds_read_b128 v[198:201], v182
	ds_read_b128 v[202:205], v182 offset:2304
	ds_read_b128 v[178:181], v183 offset:36864
	ds_read_b128 v[186:189], v183 offset:39168
	ds_read_b128 v[190:193], v183 offset:41472
	ds_read_b128 v[194:197], v183 offset:43776
	.p2align 6

; DI f32x4 mfma16(bf16x8 a, bf16x8 b, f32x4 c) { return __builtin_amdgcn_mfma_f32_16x16x32_bf16(a, b, c, 0, 0, 0); }
; template <int MI, int NJ, bool SWAP, class AP, class BP>
; DI void gemm_main(f32x4 (&acc)[MI][NJ], const AP& ap, int a_kstep, const BP& bp, int b_kstep, int nk, bf16_t* smem) {
;     ...
;   for (int kt = 0; kt < nk; ++kt) {
;     const int buf = kt & 1;
;     sstore(buf ^ 1);
;     gload(kt + 2 < nk ? kt + 2 : nk - 1);
;     __builtin_amdgcn_sched_barrier(0);
;     const bf16_t* As = smem + buf * L::STAGE + (wm * 16 * MI + l15) * LDT + quad * 8;
;     const bf16_t* Bs = smem + buf * L::STAGE + L::A_ELEMS + (wn * 16 * NJ + l15) * LDT + quad * 8;
; #pragma unroll
;     for (int ks = 0; ks < 2; ++ks) {
;       if (MI * NJ >= 32 && ks == 1) asm volatile("" ::: "memory");
;       bf16x8 b[NJ];
; #pragma unroll
;       for (int j = 0; j < NJ; ++j) b[j] = *(const bf16x8*)(Bs + j * 16 * LDT + ks * 32);
; #pragma unroll
;       for (int i = 0; i < MI; ++i) {
;         const bf16x8 a = *(const bf16x8*)(As + i * 16 * LDT + ks * 32);
; #pragma unroll
;         for (int j = 0; j < NJ; ++j) acc[i][j] = SWAP ? mfma16(b[j], a, acc[i][j]) : mfma16(a, b[j], acc[i][j]);
.LBB0_400:
	s_and_b32 s98, s5, 1
	s_mul_i32 s98, s98, 0x12000
	v_add3_u32 v182, s98, v176, v177
	v_add3_u32 v183, s98, v171, v177
	ds_read_b128 v[198:201], v182
	ds_read_b128 v[202:205], v182 offset:2304
	ds_read_b128 v[178:181], v183 offset:36864
	ds_read_b128 v[186:189], v183 offset:39168
	ds_read_b128 v[190:193], v183 offset:41472
	ds_read_b128 v[194:197], v183 offset:43776
	.p2align 6

; DI f32x4 mfma16(bf16x8 a, bf16x8 b, f32x4 c) { return __builtin_amdgcn_mfma_f32_16x16x32_bf16(a, b, c, 0, 0, 0); }
; template <int MI, int NJ, bool SWAP, class AP, class BP>
; DI void gemm_main(f32x4 (&acc)[MI][NJ], const AP& ap, int a_kstep, const BP& bp, int b_kstep, int nk, bf16_t* smem) {
;     ...
;   for (int kt = 0; kt < nk; ++kt) {
;     const int buf = kt & 1;
;     sstore(buf ^ 1);
;     gload(kt + 2 < nk ? kt + 2 : nk - 1);
;     __builtin_amdgcn_sched_barrier(0);
;     const bf16_t* As = smem + buf * L::STAGE + (wm * 16 * MI + l15) * LDT + quad * 8;
;     const bf16_t* Bs = smem + buf * L::STAGE + L::A_ELEMS + (wn * 16 * NJ + l15) * LDT + quad * 8;
; #pragma unroll
;     for (int ks = 0; ks < 2; ++ks) {
;       if (MI * NJ >= 32 && ks == 1) asm volatile("" ::: "memory");
;       bf16x8 b[NJ];
; #pragma unroll
;       for (int j = 0; j < NJ; ++j) b[j] = *(const bf16x8*)(Bs + j * 16 * LDT + ks * 32);
; #pragma unroll
;       for (int i = 0; i < MI; ++i) {
;         const bf16x8 a = *(const bf16x8*)(As + i * 16 * LDT + ks * 32);
; #pragma unroll
;         for (int j = 0; j < NJ; ++j) acc[i][j] = SWAP ? mfma16(b[j], a, acc[i][j]) : mfma16(a, b[j], acc[i][j]);
.LBB0_405:
	s_and_b32 s98, s14, 1
	s_mul_i32 s98, s98, 0xd800
	v_add3_u32 v144, s98, v102, v107
	v_add3_u32 v156, s98, v101, v107
	ds_read_b128 v[124:127], v156
	ds_read_b128 v[128:131], v156 offset:2304
	ds_read_b128 v[108:111], v144 offset:18432
	ds_read_b128 v[112:115], v144 offset:20736
	ds_read_b128 v[116:119], v144 offset:23040
	ds_read_b128 v[120:123], v144 offset:25344
	.p2align 6

; DI void merge_tile(const Params& p, int layer, int tm, int tn, bf16_t* smem) {
;     ...
;     for (int kt = 0; kt < nk; ++kt) {
;       sstore(buf ^ 1);
;       gload_next();
;       __builtin_amdgcn_sched_barrier(0);
;       const bf16_t* As = smem + buf * L::STAGE + (wm * 128 + l15) * LDT + quad * 8;
;       const bf16_t* Bs = smem + buf * L::STAGE + L::A_ELEMS + (wn * 32 + l15) * LDT + quad * 8;
; #pragma unroll
;       for (int ks = 0; ks < 2; ++ks) {
;         if (ks == 1) asm volatile("" ::: "memory");
;         bf16x8 b[2];
; #pragma unroll
;         for (int j = 0; j < 2; ++j) b[j] = *(const bf16x8*)(Bs + j * 16 * LDT + ks * 32);
; #pragma unroll
;         for (int i = 0; i < 8; ++i) {
;           const bf16x8 a = *(const bf16x8*)(As + i * 16 * LDT + ks * 32);
.LBB0_836:
	s_mul_i32 s98, s45, 0xd800
	v_add3_u32 v164, s98, v231, v236
	v_add3_u32 v165, s98, v230, v236
	ds_read_b128 v[156:159], v165
	ds_read_b128 v[166:169], v165 offset:2304
	ds_read_b128 v[170:173], v165 offset:4608
	ds_read_b128 v[174:177], v165 offset:6912
	ds_read_b128 v[152:155], v164 offset:36864
	ds_read_b128 v[160:163], v164 offset:39168
	.p2align 6

; DI f32x4 mfma16(bf16x8 a, bf16x8 b, f32x4 c) { return __builtin_amdgcn_mfma_f32_16x16x32_bf16(a, b, c, 0, 0, 0); }
; template <int MI, int NJ, bool SWAP, class AP, class BP>
; DI void gemm_main(f32x4 (&acc)[MI][NJ], const AP& ap, int a_kstep, const BP& bp, int b_kstep, int nk, bf16_t* smem) {
;     ...
;   for (int kt = 0; kt < nk; ++kt) {
;     const int buf = kt & 1;
;     sstore(buf ^ 1);
;     gload(kt + 2 < nk ? kt + 2 : nk - 1);
;     __builtin_amdgcn_sched_barrier(0);
;     const bf16_t* As = smem + buf * L::STAGE + (wm * 16 * MI + l15) * LDT + quad * 8;
;     const bf16_t* Bs = smem + buf * L::STAGE + L::A_ELEMS + (wn * 16 * NJ + l15) * LDT + quad * 8;
; #pragma unroll
;     for (int ks = 0; ks < 2; ++ks) {
;       if (MI * NJ >= 32 && ks == 1) asm volatile("" ::: "memory");
;       bf16x8 b[NJ];
; #pragma unroll
;       for (int j = 0; j < NJ; ++j) b[j] = *(const bf16x8*)(Bs + j * 16 * LDT + ks * 32);
; #pragma unroll
;       for (int i = 0; i < MI; ++i) {
;         const bf16x8 a = *(const bf16x8*)(As + i * 16 * LDT + ks * 32);
; #pragma unroll
;         for (int j = 0; j < NJ; ++j) acc[i][j] = SWAP ? mfma16(b[j], a, acc[i][j]) : mfma16(a, b[j], acc[i][j]);
.LBB0_910:
	s_and_b32 s98, s1, 1
	s_mul_i32 s98, s98, 0x12000
	v_add3_u32 v202, s98, v160, v173
	v_add3_u32 v177, s98, v171, v173
	ds_read_b128 v[194:197], v177
	ds_read_b128 v[198:201], v177 offset:2304
	ds_read_b128 v[178:181], v202 offset:36864
	ds_read_b128 v[182:185], v202 offset:39168
	ds_read_b128 v[186:189], v202 offset:41472
	ds_read_b128 v[190:193], v202 offset:43776
	.p2align 6

; DI f32x4 mfma16(bf16x8 a, bf16x8 b, f32x4 c) { return __builtin_amdgcn_mfma_f32_16x16x32_bf16(a, b, c, 0, 0, 0); }
; template <int MI, int NJ, bool SWAP, class AP, class BP>
; DI void gemm_main(f32x4 (&acc)[MI][NJ], const AP& ap, int a_kstep, const BP& bp, int b_kstep, int nk, bf16_t* smem) {
;     ...
;   for (int kt = 0; kt < nk; ++kt) {
;     const int buf = kt & 1;
;     sstore(buf ^ 1);
;     gload(kt + 2 < nk ? kt + 2 : nk - 1);
;     __builtin_amdgcn_sched_barrier(0);
;     const bf16_t* As = smem + buf * L::STAGE + (wm * 16 * MI + l15) * LDT + quad * 8;
;     const bf16_t* Bs = smem + buf * L::STAGE + L::A_ELEMS + (wn * 16 * NJ + l15) * LDT + quad * 8;
; #pragma unroll
;     for (int ks = 0; ks < 2; ++ks) {
;       if (MI * NJ >= 32 && ks == 1) asm volatile("" ::: "memory");
;       bf16x8 b[NJ];
; #pragma unroll
;       for (int j = 0; j < NJ; ++j) b[j] = *(const bf16x8*)(Bs + j * 16 * LDT + ks * 32);
; #pragma unroll
;       for (int i = 0; i < MI; ++i) {
;         const bf16x8 a = *(const bf16x8*)(As + i * 16 * LDT + ks * 32);
; #pragma unroll
;         for (int j = 0; j < NJ; ++j) acc[i][j] = SWAP ? mfma16(b[j], a, acc[i][j]) : mfma16(a, b[j], acc[i][j]);
.LBB0_1049:
	s_cmp_eq_u32 s29, 0xfde
	s_cbranch_scc1 .Lgm6r_main
	s_and_b32 s98, s30, 1
	s_mul_i32 s98, s98, 0x12000
	v_add3_u32 v181, s98, v170, v180
	v_add3_u32 v202, s98, v171, v180
	ds_read_b128 v[198:201], v181
	ds_read_b128 v[242:245], v181 offset:2304
	ds_read_b128 v[182:185], v202 offset:36864
	ds_read_b128 v[186:189], v202 offset:39168
	ds_read_b128 v[190:193], v202 offset:41472
	ds_read_b128 v[194:197], v202 offset:43776
	.p2align 6

; DI f32x4 mfma16(bf16x8 a, bf16x8 b, f32x4 c) { return __builtin_amdgcn_mfma_f32_16x16x32_bf16(a, b, c, 0, 0, 0); }
; template <int MI, int NJ, bool SWAP, class AP, class BP>
; DI void gemm_main(f32x4 (&acc)[MI][NJ], const AP& ap, int a_kstep, const BP& bp, int b_kstep, int nk, bf16_t* smem) {
;     ...
;   for (int kt = 0; kt < nk; ++kt) {
;     const int buf = kt & 1;
;     sstore(buf ^ 1);
;     gload(kt + 2 < nk ? kt + 2 : nk - 1);
;     __builtin_amdgcn_sched_barrier(0);
;     const bf16_t* As = smem + buf * L::STAGE + (wm * 16 * MI + l15) * LDT + quad * 8;
;     const bf16_t* Bs = smem + buf * L::STAGE + L::A_ELEMS + (wn * 16 * NJ + l15) * LDT + quad * 8;
; #pragma unroll
;     for (int ks = 0; ks < 2; ++ks) {
;       if (MI * NJ >= 32 && ks == 1) asm volatile("" ::: "memory");
;       bf16x8 b[NJ];
; #pragma unroll
;       for (int j = 0; j < NJ; ++j) b[j] = *(const bf16x8*)(Bs + j * 16 * LDT + ks * 32);
; #pragma unroll
;       for (int i = 0; i < MI; ++i) {
;         const bf16x8 a = *(const bf16x8*)(As + i * 16 * LDT + ks * 32);
; #pragma unroll
;         for (int j = 0; j < NJ; ++j) acc[i][j] = SWAP ? mfma16(b[j], a, acc[i][j]) : mfma16(a, b[j], acc[i][j]);
.LBB0_1128:
	s_and_b32 s98, s21, 1
	s_mul_i32 s98, s98, 0x12000
	v_add3_u32 v202, s98, v160, v176
	v_add3_u32 v177, s98, v171, v176
	ds_read_b128 v[194:197], v177
	ds_read_b128 v[198:201], v177 offset:2304
	ds_read_b128 v[178:181], v202 offset:36864
	ds_read_b128 v[182:185], v202 offset:39168
	ds_read_b128 v[186:189], v202 offset:41472
	ds_read_b128 v[190:193], v202 offset:43776
	.p2align 6

; DI f32x4 mfma16(bf16x8 a, bf16x8 b, f32x4 c) { return __builtin_amdgcn_mfma_f32_16x16x32_bf16(a, b, c, 0, 0, 0); }
; template <int MI, int NJ, bool SWAP, class AP, class BP>
; DI void gemm_main(f32x4 (&acc)[MI][NJ], const AP& ap, int a_kstep, const BP& bp, int b_kstep, int nk, bf16_t* smem) {
;     ...
;   for (int kt = 0; kt < nk; ++kt) {
;     const int buf = kt & 1;
;     sstore(buf ^ 1);
;     gload(kt + 2 < nk ? kt + 2 : nk - 1);
;     __builtin_amdgcn_sched_barrier(0);
;     const bf16_t* As = smem + buf * L::STAGE + (wm * 16 * MI + l15) * LDT + quad * 8;
;     const bf16_t* Bs = smem + buf * L::STAGE + L::A_ELEMS + (wn * 16 * NJ + l15) * LDT + quad * 8;
; #pragma unroll
;     for (int ks = 0; ks < 2; ++ks) {
;       if (MI * NJ >= 32 && ks == 1) asm volatile("" ::: "memory");
;       bf16x8 b[NJ];
; #pragma unroll
;       for (int j = 0; j < NJ; ++j) b[j] = *(const bf16x8*)(Bs + j * 16 * LDT + ks * 32);
; #pragma unroll
;       for (int i = 0; i < MI; ++i) {
;         const bf16x8 a = *(const bf16x8*)(As + i * 16 * LDT + ks * 32);
; #pragma unroll
;         for (int j = 0; j < NJ; ++j) acc[i][j] = SWAP ? mfma16(b[j], a, acc[i][j]) : mfma16(a, b[j], acc[i][j]);
.LBB0_1208:
	s_and_b32 s98, s4, 1
	s_mul_i32 s98, s98, 0x12000
	v_add3_u32 v210, s98, v184, v186
	v_add3_u32 v211, s98, v160, v186
	ds_read_b128 v[206:209], v210
	ds_read_b128 v[242:245], v210 offset:2304
	ds_read_b128 v[190:193], v211 offset:36864
	ds_read_b128 v[194:197], v211 offset:39168
	ds_read_b128 v[198:201], v211 offset:41472
	ds_read_b128 v[202:205], v211 offset:43776
	.p2align 6

; DI f32x4 mfma16(bf16x8 a, bf16x8 b, f32x4 c) { return __builtin_amdgcn_mfma_f32_16x16x32_bf16(a, b, c, 0, 0, 0); }
; template <int MI, int NJ, bool SWAP, class AP, class BP>
; DI void gemm_main(f32x4 (&acc)[MI][NJ], const AP& ap, int a_kstep, const BP& bp, int b_kstep, int nk, bf16_t* smem) {
;     ...
;   for (int kt = 0; kt < nk; ++kt) {
;     const int buf = kt & 1;
;     sstore(buf ^ 1);
;     gload(kt + 2 < nk ? kt + 2 : nk - 1);
;     __builtin_amdgcn_sched_barrier(0);
;     const bf16_t* As = smem + buf * L::STAGE + (wm * 16 * MI + l15) * LDT + quad * 8;
;     const bf16_t* Bs = smem + buf * L::STAGE + L::A_ELEMS + (wn * 16 * NJ + l15) * LDT + quad * 8;
; #pragma unroll
;     for (int ks = 0; ks < 2; ++ks) {
;       if (MI * NJ >= 32 && ks == 1) asm volatile("" ::: "memory");
;       bf16x8 b[NJ];
; #pragma unroll
;       for (int j = 0; j < NJ; ++j) b[j] = *(const bf16x8*)(Bs + j * 16 * LDT + ks * 32);
; #pragma unroll
;       for (int i = 0; i < MI; ++i) {
;         const bf16x8 a = *(const bf16x8*)(As + i * 16 * LDT + ks * 32);
; #pragma unroll
;         for (int j = 0; j < NJ; ++j) acc[i][j] = SWAP ? mfma16(b[j], a, acc[i][j]) : mfma16(a, b[j], acc[i][j]);
.LBB0_1331:
	s_and_b32 s98, s4, 1
	s_mul_i32 s98, s98, 0x12000
	v_add3_u32 v210, s98, v188, v189
	v_add3_u32 v211, s98, v183, v189
	ds_read_b128 v[206:209], v210
	ds_read_b128 v[242:245], v210 offset:2304
	ds_read_b128 v[190:193], v211 offset:36864
	ds_read_b128 v[194:197], v211 offset:39168
	ds_read_b128 v[198:201], v211 offset:41472
	ds_read_b128 v[202:205], v211 offset:43776
	.p2align 6

; DI f32x4 mfma16(bf16x8 a, bf16x8 b, f32x4 c) { return __builtin_amdgcn_mfma_f32_16x16x32_bf16(a, b, c, 0, 0, 0); }
; template <int MI, int NJ, bool SWAP, class AP, class BP>
; DI void gemm_main(f32x4 (&acc)[MI][NJ], const AP& ap, int a_kstep, const BP& bp, int b_kstep, int nk, bf16_t* smem) {
;     ...
;   for (int kt = 0; kt < nk; ++kt) {
;     const int buf = kt & 1;
;     sstore(buf ^ 1);
;     gload(kt + 2 < nk ? kt + 2 : nk - 1);
;     __builtin_amdgcn_sched_barrier(0);
;     const bf16_t* As = smem + buf * L::STAGE + (wm * 16 * MI + l15) * LDT + quad * 8;
;     const bf16_t* Bs = smem + buf * L::STAGE + L::A_ELEMS + (wn * 16 * NJ + l15) * LDT + quad * 8;
; #pragma unroll
;     for (int ks = 0; ks < 2; ++ks) {
;       if (MI * NJ >= 32 && ks == 1) asm volatile("" ::: "memory");
;       bf16x8 b[NJ];
; #pragma unroll
;       for (int j = 0; j < NJ; ++j) b[j] = *(const bf16x8*)(Bs + j * 16 * LDT + ks * 32);
; #pragma unroll
;       for (int i = 0; i < MI; ++i) {
;         const bf16x8 a = *(const bf16x8*)(As + i * 16 * LDT + ks * 32);
; #pragma unroll
;         for (int j = 0; j < NJ; ++j) acc[i][j] = SWAP ? mfma16(b[j], a, acc[i][j]) : mfma16(a, b[j], acc[i][j]);
.LBB0_1410:
	s_and_b32 s98, s8, 1
	s_mul_i32 s98, s98, 0x12000
	v_add3_u32 v198, s98, v172, v177
	v_add3_u32 v199, s98, v160, v177
	ds_read_b128 v[194:197], v198
	ds_read_b128 v[242:245], v198 offset:2304
	ds_read_b128 v[178:181], v199 offset:36864
	ds_read_b128 v[182:185], v199 offset:39168
	ds_read_b128 v[186:189], v199 offset:41472
	ds_read_b128 v[190:193], v199 offset:43776
	.p2align 6

; DI f32x4 mfma16(bf16x8 a, bf16x8 b, f32x4 c) { return __builtin_amdgcn_mfma_f32_16x16x32_bf16(a, b, c, 0, 0, 0); }
; template <int MI, int NJ, bool SWAP, class AP, class BP>
; DI void gemm_main(f32x4 (&acc)[MI][NJ], const AP& ap, int a_kstep, const BP& bp, int b_kstep, int nk, bf16_t* smem) {
;     ...
;   for (int kt = 0; kt < nk; ++kt) {
;     const int buf = kt & 1;
;     sstore(buf ^ 1);
;     gload(kt + 2 < nk ? kt + 2 : nk - 1);
;     __builtin_amdgcn_sched_barrier(0);
;     const bf16_t* As = smem + buf * L::STAGE + (wm * 16 * MI + l15) * LDT + quad * 8;
;     const bf16_t* Bs = smem + buf * L::STAGE + L::A_ELEMS + (wn * 16 * NJ + l15) * LDT + quad * 8;
; #pragma unroll
;     for (int ks = 0; ks < 2; ++ks) {
;       if (MI * NJ >= 32 && ks == 1) asm volatile("" ::: "memory");
;       bf16x8 b[NJ];
; #pragma unroll
;       for (int j = 0; j < NJ; ++j) b[j] = *(const bf16x8*)(Bs + j * 16 * LDT + ks * 32);
; #pragma unroll
;       for (int i = 0; i < MI; ++i) {
;         const bf16x8 a = *(const bf16x8*)(As + i * 16 * LDT + ks * 32);
; #pragma unroll
;         for (int j = 0; j < NJ; ++j) acc[i][j] = SWAP ? mfma16(b[j], a, acc[i][j]) : mfma16(a, b[j], acc[i][j]);
.LBB0_1430:
	s_and_b32 s98, s33, 1
	s_mul_i32 s98, s98, 0x12000
	v_add3_u32 v198, s98, v176, v177
	v_add3_u32 v199, s98, v171, v177
	ds_read_b128 v[194:197], v198
	ds_read_b128 v[242:245], v198 offset:2304
	ds_read_b128 v[178:181], v199 offset:36864
	ds_read_b128 v[182:185], v199 offset:39168
	ds_read_b128 v[186:189], v199 offset:41472
	ds_read_b128 v[190:193], v199 offset:43776
	.p2align 6

; DI f32x4 mfma16(bf16x8 a, bf16x8 b, f32x4 c) { return __builtin_amdgcn_mfma_f32_16x16x32_bf16(a, b, c, 0, 0, 0); }
; template <int MI, int NJ, bool SWAP, class AP, class BP>
; DI void gemm_main(f32x4 (&acc)[MI][NJ], const AP& ap, int a_kstep, const BP& bp, int b_kstep, int nk, bf16_t* smem) {
;     ...
;   for (int kt = 0; kt < nk; ++kt) {
;     const int buf = kt & 1;
;     sstore(buf ^ 1);
;     gload(kt + 2 < nk ? kt + 2 : nk - 1);
;     __builtin_amdgcn_sched_barrier(0);
;     const bf16_t* As = smem + buf * L::STAGE + (wm * 16 * MI + l15) * LDT + quad * 8;
;     const bf16_t* Bs = smem + buf * L::STAGE + L::A_ELEMS + (wn * 16 * NJ + l15) * LDT + quad * 8;
; #pragma unroll
;     for (int ks = 0; ks < 2; ++ks) {
;       if (MI * NJ >= 32 && ks == 1) asm volatile("" ::: "memory");
;       bf16x8 b[NJ];
; #pragma unroll
;       for (int j = 0; j < NJ; ++j) b[j] = *(const bf16x8*)(Bs + j * 16 * LDT + ks * 32);
; #pragma unroll
;       for (int i = 0; i < MI; ++i) {
;         const bf16x8 a = *(const bf16x8*)(As + i * 16 * LDT + ks * 32);
; #pragma unroll
;         for (int j = 0; j < NJ; ++j) acc[i][j] = SWAP ? mfma16(b[j], a, acc[i][j]) : mfma16(a, b[j], acc[i][j]);
.LBB0_1434:
	s_and_b32 s98, s8, 1
	s_mul_i32 s98, s98, 0x12000
	v_add3_u32 v198, s98, v176, v177
	v_add3_u32 v199, s98, v171, v177
	ds_read_b128 v[194:197], v198
	ds_read_b128 v[242:245], v198 offset:2304
	ds_read_b128 v[178:181], v199 offset:36864
	ds_read_b128 v[182:185], v199 offset:39168
	ds_read_b128 v[186:189], v199 offset:41472
	ds_read_b128 v[190:193], v199 offset:43776
	.p2align 6

; DI void merge_tile(const Params& p, int layer, int tm, int tn, bf16_t* smem) {
;     ...
;     for (int kt = 0; kt < nk; ++kt) {
;       sstore(buf ^ 1);
;       gload_next();
;       __builtin_amdgcn_sched_barrier(0);
;       const bf16_t* As = smem + buf * L::STAGE + (wm * 128 + l15) * LDT + quad * 8;
;       const bf16_t* Bs = smem + buf * L::STAGE + L::A_ELEMS + (wn * 32 + l15) * LDT + quad * 8;
; #pragma unroll
;       for (int ks = 0; ks < 2; ++ks) {
;         if (ks == 1) asm volatile("" ::: "memory");
;         bf16x8 b[2];
; #pragma unroll
;         for (int j = 0; j < 2; ++j) b[j] = *(const bf16x8*)(Bs + j * 16 * LDT + ks * 32);
; #pragma unroll
;         for (int i = 0; i < 8; ++i) {
;           const bf16x8 a = *(const bf16x8*)(As + i * 16 * LDT + ks * 32);
.LBB0_1870:
	s_mul_i32 s98, s57, 0xd800
	v_add3_u32 v164, s98, v231, v236
	v_add3_u32 v168, s98, v230, v236
	ds_read_b128 v[156:159], v168
	ds_read_b128 v[170:173], v168 offset:2304
	ds_read_b128 v[174:177], v168 offset:4608
	ds_read_b128 v[178:181], v168 offset:6912
	ds_read_b128 v[152:155], v164 offset:36864
	ds_read_b128 v[160:163], v164 offset:39168
	.p2align 6

; DI f32x4 mfma16(bf16x8 a, bf16x8 b, f32x4 c) { return __builtin_amdgcn_mfma_f32_16x16x32_bf16(a, b, c, 0, 0, 0); }
; template <int MI, int NJ, bool SWAP, class AP, class BP>
; DI void gemm_main(f32x4 (&acc)[MI][NJ], const AP& ap, int a_kstep, const BP& bp, int b_kstep, int nk, bf16_t* smem) {
;     ...
;   for (int kt = 0; kt < nk; ++kt) {
;     const int buf = kt & 1;
;     sstore(buf ^ 1);
;     gload(kt + 2 < nk ? kt + 2 : nk - 1);
;     __builtin_amdgcn_sched_barrier(0);
;     const bf16_t* As = smem + buf * L::STAGE + (wm * 16 * MI + l15) * LDT + quad * 8;
;     const bf16_t* Bs = smem + buf * L::STAGE + L::A_ELEMS + (wn * 16 * NJ + l15) * LDT + quad * 8;
; #pragma unroll
;     for (int ks = 0; ks < 2; ++ks) {
;       if (MI * NJ >= 32 && ks == 1) asm volatile("" ::: "memory");
;       bf16x8 b[NJ];
; #pragma unroll
;       for (int j = 0; j < NJ; ++j) b[j] = *(const bf16x8*)(Bs + j * 16 * LDT + ks * 32);
; #pragma unroll
;       for (int i = 0; i < MI; ++i) {
;         const bf16x8 a = *(const bf16x8*)(As + i * 16 * LDT + ks * 32);
; #pragma unroll
;         for (int j = 0; j < NJ; ++j) acc[i][j] = SWAP ? mfma16(b[j], a, acc[i][j]) : mfma16(a, b[j], acc[i][j]);
.LBB0_2083:
	s_cmp_eq_u32 s42, 0xfde
	s_cbranch_scc1 .Lgm14r_main
	s_and_b32 s98, s43, 1
	s_mul_i32 s98, s98, 0x12000
	v_add3_u32 v206, s98, v171, v180
	v_add3_u32 v181, s98, v170, v180
	ds_read_b128 v[198:201], v181
	ds_read_b128 v[202:205], v181 offset:2304
	ds_read_b128 v[182:185], v206 offset:36864
	ds_read_b128 v[186:189], v206 offset:39168
	ds_read_b128 v[190:193], v206 offset:41472
	ds_read_b128 v[194:197], v206 offset:43776
	.p2align 6

; DI f32x4 mfma16(bf16x8 a, bf16x8 b, f32x4 c) { return __builtin_amdgcn_mfma_f32_16x16x32_bf16(a, b, c, 0, 0, 0); }
; template <int MI, int NJ, bool SWAP, class AP, class BP>
; DI void gemm_main(f32x4 (&acc)[MI][NJ], const AP& ap, int a_kstep, const BP& bp, int b_kstep, int nk, bf16_t* smem) {
;     ...
;   for (int kt = 0; kt < nk; ++kt) {
;     const int buf = kt & 1;
;     sstore(buf ^ 1);
;     gload(kt + 2 < nk ? kt + 2 : nk - 1);
;     __builtin_amdgcn_sched_barrier(0);
;     const bf16_t* As = smem + buf * L::STAGE + (wm * 16 * MI + l15) * LDT + quad * 8;
;     const bf16_t* Bs = smem + buf * L::STAGE + L::A_ELEMS + (wn * 16 * NJ + l15) * LDT + quad * 8;
; #pragma unroll
;     for (int ks = 0; ks < 2; ++ks) {
;       if (MI * NJ >= 32 && ks == 1) asm volatile("" ::: "memory");
;       bf16x8 b[NJ];
; #pragma unroll
;       for (int j = 0; j < NJ; ++j) b[j] = *(const bf16x8*)(Bs + j * 16 * LDT + ks * 32);
; #pragma unroll
;       for (int i = 0; i < MI; ++i) {
;         const bf16x8 a = *(const bf16x8*)(As + i * 16 * LDT + ks * 32);
; #pragma unroll
;         for (int j = 0; j < NJ; ++j) acc[i][j] = SWAP ? mfma16(b[j], a, acc[i][j]) : mfma16(a, b[j], acc[i][j]);
.LBB0_2163:
	s_and_b32 s98, s16, 1
	s_mul_i32 s98, s98, 0x12000
	v_add3_u32 v202, s98, v160, v176
	v_add3_u32 v177, s98, v171, v176
	ds_read_b128 v[194:197], v177
	ds_read_b128 v[198:201], v177 offset:2304
	ds_read_b128 v[178:181], v202 offset:36864
	ds_read_b128 v[182:185], v202 offset:39168
	ds_read_b128 v[186:189], v202 offset:41472
	ds_read_b128 v[190:193], v202 offset:43776
	.p2align 6
